# v11: v8 + residual GEMM epilogues re-emitted as a 3-deep ring of 4-load half-groups (loads never wait behind write-through stores)
# baseline (speedup 1.0000x reference)
;   DI void operator()(const f4 (&acc)[2][2][4][2], const GUnit& u, int wr, int wc, int fr, int fq) const {
;     ...
;     const int g0 = row0_of(u.pm, isctx ? 2 : 1), b = g0 / TOK, t0 = g0 - b * TOK;
;     const int col0 = u.pn * 256 + wc * 32;
;     const size_t rowoff = (size_t)(wr * 64) * 1024 + col0;
;     const char* src = (const char*)(xl_src + ((size_t)b * SEQ + (isctx ? 0 : t0)) * 1024 + rowoff);
;     char* dst = (char*)(xl_dst + ((size_t)b * SEQ + (isctx ? 0 : t0)) * 1024 + rowoff);
;     const char* gt = (const char*)(mods_l + (size_t)(isctx ? 16 : b) * 6144 + gt_off + col0);
;     const unsigned lo = (unsigned)(fr * 1024 + 4 * fq) * 4u, glo = (unsigned)(4 * fq) * 4u;
;     f4 gv[2][2];
; #pragma unroll
;     for (int bj = 0; bj < 2; ++bj)
; #pragma unroll
;       for (int n = 0; n < 2; ++n) gv[bj][n] = *(const f4*)(gt + (bj * 128 + n * 16) * 4 + glo);
;     if (!isctx) {
; #pragma unroll
;       for (int ai = 0; ai < 2; ++ai)
; #pragma unroll
;         for (int mh = 0; mh < 2; ++mh) {
;           f4 xv[2][2][2];
; #pragma unroll
;           for (int mm = 0; mm < 2; ++mm)
; #pragma unroll
;             for (int bj = 0; bj < 2; ++bj)
; #pragma unroll
;               for (int n = 0; n < 2; ++n)
;                 xv[mm][bj][n] = *(const f4*)(src + ((size_t)(ai * 128 + (mh * 2 + mm) * 16) * 1024 + bj * 128 + n * 16) * 4 + lo);
; #pragma unroll
;           for (int mm = 0; mm < 2; ++mm)
; #pragma unroll
;             for (int bj = 0; bj < 2; ++bj)
; #pragma unroll
;               for (int n = 0; n < 2; ++n)
;                 wt16(dst + ((size_t)(ai * 128 + (mh * 2 + mm) * 16) * 1024 + bj * 128 + n * 16) * 4, lo, as_u4(xv[mm][bj][n] + gv[bj][n] * acc[ai][bj][mh * 2 + mm][n]));
;         }
.LBB0_2440:
	s_mul_hi_i32 s18, s9, 0x38e38e39
	s_lshr_b32 s19, s18, 31
	s_ashr_i32 s18, s18, 9
	s_add_i32 s18, s18, s19
	s_mul_i32 s19, s18, 0xfffff700
	s_add_i32 s22, s19, s9
	s_lshl_b32 s9, s17, 8
	s_or_b32 s26, s9, s68
	s_ashr_i32 s27, s26, 31
	s_ashr_i32 s19, s18, 31
	s_and_b64 s[20:21], exec, s[20:21]
	s_cselect_b32 s9, 16, s18
	s_mul_hi_i32 s17, s9, 0x6000
	s_mulk_i32 s9, 0x6000
	s_add_u32 s9, s38, s9
	s_addc_u32 s17, s39, s17
	s_lshl_b64 s[20:21], s[26:27], 2
	s_add_u32 s74, s9, s20
	s_addc_u32 s75, s17, s21
	s_waitcnt vmcnt(0)
	v_lshl_add_u64 v[130:131], s[74:75], 0, v[154:155]
	s_mov_b64 s[74:75], 0x2000
	v_lshl_add_u64 v[132:133], v[130:131], 0, s[74:75]
	v_add_co_u32_e32 v130, vcc, 0x2000, v130
	s_nop 1
	v_addc_co_u32_e32 v131, vcc, 0, v131, vcc
	global_load_dwordx4 v[138:141], v[132:133], off offset:64
	global_load_dwordx4 v[134:137], v[132:133], off offset:512
	global_load_dwordx4 v[142:145], v[130:131], off
	s_nop 0
	global_load_dwordx4 v[130:133], v[132:133], off offset:576
	s_andn2_b64 vcc, exec, s[24:25]
	s_mov_b64 s[24:25], -1
	s_cbranch_vccnz .LBB0_2442
	s_ashr_i32 s23, s22, 31
	s_lshl_b64 s[24:25], s[22:23], 10
	s_lshl_b64 s[74:75], s[18:19], 21
	s_add_u32 s24, s24, s74
	s_addc_u32 s25, s25, s75
	s_lshl_b64 s[74:75], s[24:25], 2
	s_waitcnt lgkmcnt(0)
	s_add_u32 s9, s2, s74
	s_addc_u32 s17, s3, s75
	s_add_u32 s24, s6, s26
	s_addc_u32 s25, s7, s27
	s_lshl_b64 s[26:27], s[24:25], 2
	s_add_u32 s24, s9, s26
	s_addc_u32 s25, s17, s27
	v_readlane_b32 s40, v254, 55
	v_readlane_b32 s41, v254, 56
	s_add_u32 s9, s40, s74
	s_addc_u32 s17, s41, s75
	s_add_u32 s26, s9, s26
	s_addc_u32 s27, s17, s27
	v_lshl_add_u64 v[146:147], s[26:27], 0, v[156:157]
	global_load_dwordx4 v[164:167], v[146:147], off
	global_load_dwordx4 v[168:171], v[146:147], off offset:64
	global_load_dwordx4 v[172:175], v[146:147], off offset:512
	global_load_dwordx4 v[176:179], v[146:147], off offset:576
	v_add_co_u32_e32 v148, vcc, 0x10000, v146
	s_nop 1
	v_addc_co_u32_e32 v149, vcc, 0, v147, vcc
	global_load_dwordx4 v[180:183], v[148:149], off
	global_load_dwordx4 v[184:187], v[148:149], off offset:64
	global_load_dwordx4 v[188:191], v[148:149], off offset:512
	global_load_dwordx4 v[192:195], v[148:149], off offset:576
	v_add_co_u32_e32 v148, vcc, 0x20000, v146
	s_nop 1
	v_addc_co_u32_e32 v149, vcc, 0, v147, vcc
	global_load_dwordx4 v[196:199], v[148:149], off
	global_load_dwordx4 v[200:203], v[148:149], off offset:64
	global_load_dwordx4 v[204:207], v[148:149], off offset:512
	global_load_dwordx4 v[208:211], v[148:149], off offset:576
	s_waitcnt vmcnt(11)
	v_pk_fma_f32 v[166:167], v[128:129], v[144:145], v[166:167]
	v_pk_fma_f32 v[164:165], v[126:127], v[142:143], v[164:165]
	s_nop 0
	global_store_dwordx4 v156, v[164:167], s[24:25] sc1
	s_nop 1
	s_waitcnt vmcnt(11)
	v_pk_fma_f32 v[170:171], v[124:125], v[140:141], v[170:171]
	v_pk_fma_f32 v[168:169], v[122:123], v[138:139], v[168:169]
	s_add_u32 s26, s24, 0x40
	s_addc_u32 s27, s25, 0
	s_nop 0
	global_store_dwordx4 v156, v[168:171], s[26:27] sc1
	s_nop 1
	s_waitcnt vmcnt(11)
	v_pk_fma_f32 v[174:175], v[120:121], v[136:137], v[174:175]
	v_pk_fma_f32 v[172:173], v[118:119], v[134:135], v[172:173]
	s_add_u32 s26, s24, 0x200
	s_addc_u32 s27, s25, 0
	s_nop 0
	global_store_dwordx4 v156, v[172:175], s[26:27] sc1
	s_nop 1
	s_waitcnt vmcnt(11)
	v_pk_fma_f32 v[178:179], v[116:117], v[132:133], v[178:179]
	v_pk_fma_f32 v[176:177], v[114:115], v[130:131], v[176:177]
	s_add_u32 s26, s24, 0x240
	s_addc_u32 s27, s25, 0
	s_nop 0
	global_store_dwordx4 v156, v[176:179], s[26:27] sc1
	s_nop 1
	v_add_co_u32_e32 v148, vcc, 0x30000, v146
	s_nop 1
	v_addc_co_u32_e32 v149, vcc, 0, v147, vcc
	global_load_dwordx4 v[164:167], v[148:149], off
	global_load_dwordx4 v[168:171], v[148:149], off offset:64
	global_load_dwordx4 v[172:175], v[148:149], off offset:512
	global_load_dwordx4 v[176:179], v[148:149], off offset:576
	s_waitcnt vmcnt(15)
	v_pk_fma_f32 v[182:183], v[112:113], v[144:145], v[182:183]
	v_pk_fma_f32 v[180:181], v[110:111], v[142:143], v[180:181]
	s_add_u32 s26, s24, 0x10000
	s_addc_u32 s27, s25, 0
	s_nop 0
	global_store_dwordx4 v156, v[180:183], s[26:27] sc1
	s_nop 1
	s_waitcnt vmcnt(15)
	v_pk_fma_f32 v[186:187], v[108:109], v[140:141], v[186:187]
	v_pk_fma_f32 v[184:185], v[106:107], v[138:139], v[184:185]
	s_add_u32 s26, s24, 0x10040
	s_addc_u32 s27, s25, 0
	s_nop 0
	global_store_dwordx4 v156, v[184:187], s[26:27] sc1
	s_nop 1
	s_waitcnt vmcnt(15)
	v_pk_fma_f32 v[190:191], v[104:105], v[136:137], v[190:191]
	v_pk_fma_f32 v[188:189], v[102:103], v[134:135], v[188:189]
	s_add_u32 s26, s24, 0x10200
	s_addc_u32 s27, s25, 0
	s_nop 0
	global_store_dwordx4 v156, v[188:191], s[26:27] sc1
	s_nop 1
	s_waitcnt vmcnt(15)
	v_pk_fma_f32 v[194:195], v[100:101], v[132:133], v[194:195]
	v_pk_fma_f32 v[192:193], v[98:99], v[130:131], v[192:193]
	s_add_u32 s26, s24, 0x10240
	s_addc_u32 s27, s25, 0
	s_nop 0
	global_store_dwordx4 v156, v[192:195], s[26:27] sc1
	s_nop 1
	v_add_co_u32_e32 v148, vcc, 0x80000, v146
	s_nop 1
	v_addc_co_u32_e32 v149, vcc, 0, v147, vcc
	global_load_dwordx4 v[180:183], v[148:149], off
	global_load_dwordx4 v[184:187], v[148:149], off offset:64
	global_load_dwordx4 v[188:191], v[148:149], off offset:512
	global_load_dwordx4 v[192:195], v[148:149], off offset:576
	s_waitcnt vmcnt(19)
	v_pk_fma_f32 v[198:199], v[96:97], v[144:145], v[198:199]
	v_pk_fma_f32 v[196:197], v[94:95], v[142:143], v[196:197]
	s_add_u32 s26, s24, 0x20000
	s_addc_u32 s27, s25, 0
	s_nop 0
	global_store_dwordx4 v156, v[196:199], s[26:27] sc1
	s_nop 1
	s_waitcnt vmcnt(19)
;   DI void operator()(const f4 (&acc)[2][2][4][2], const GUnit& u, int wr, int wc, int fr, int fq) const {
;     ...
;     if (!isctx) {
; #pragma unroll
;       for (int ai = 0; ai < 2; ++ai)
; #pragma unroll
;         for (int mh = 0; mh < 2; ++mh) {
;           f4 xv[2][2][2];
; #pragma unroll
;           for (int mm = 0; mm < 2; ++mm)
; #pragma unroll
;             for (int bj = 0; bj < 2; ++bj)
; #pragma unroll
;               for (int n = 0; n < 2; ++n)
;                 xv[mm][bj][n] = *(const f4*)(src + ((size_t)(ai * 128 + (mh * 2 + mm) * 16) * 1024 + bj * 128 + n * 16) * 4 + lo);
; #pragma unroll
;           for (int mm = 0; mm < 2; ++mm)
; #pragma unroll
;             for (int bj = 0; bj < 2; ++bj)
; #pragma unroll
;               for (int n = 0; n < 2; ++n)
;                 wt16(dst + ((size_t)(ai * 128 + (mh * 2 + mm) * 16) * 1024 + bj * 128 + n * 16) * 4, lo, as_u4(xv[mm][bj][n] + gv[bj][n] * acc[ai][bj][mh * 2 + mm][n]));
;         }
	v_pk_fma_f32 v[202:203], v[92:93], v[140:141], v[202:203]
	v_pk_fma_f32 v[200:201], v[90:91], v[138:139], v[200:201]
	s_add_u32 s26, s24, 0x20040
	s_addc_u32 s27, s25, 0
	s_nop 0
	global_store_dwordx4 v156, v[200:203], s[26:27] sc1
	s_nop 1
	s_waitcnt vmcnt(19)
	v_pk_fma_f32 v[206:207], v[88:89], v[136:137], v[206:207]
	v_pk_fma_f32 v[204:205], v[86:87], v[134:135], v[204:205]
	s_add_u32 s26, s24, 0x20200
	s_addc_u32 s27, s25, 0
	s_nop 0
	global_store_dwordx4 v156, v[204:207], s[26:27] sc1
	s_nop 1
	s_waitcnt vmcnt(19)
	v_pk_fma_f32 v[210:211], v[84:85], v[132:133], v[210:211]
	v_pk_fma_f32 v[208:209], v[82:83], v[130:131], v[208:209]
	s_add_u32 s26, s24, 0x20240
	s_addc_u32 s27, s25, 0
	s_nop 0
	global_store_dwordx4 v156, v[208:211], s[26:27] sc1
	s_nop 1
	v_add_co_u32_e32 v148, vcc, 0x90000, v146
	s_nop 1
	v_addc_co_u32_e32 v149, vcc, 0, v147, vcc
	global_load_dwordx4 v[196:199], v[148:149], off
	global_load_dwordx4 v[200:203], v[148:149], off offset:64
	global_load_dwordx4 v[204:207], v[148:149], off offset:512
	global_load_dwordx4 v[208:211], v[148:149], off offset:576
	s_waitcnt vmcnt(19)
	v_pk_fma_f32 v[166:167], v[80:81], v[144:145], v[166:167]
	v_pk_fma_f32 v[164:165], v[78:79], v[142:143], v[164:165]
	s_add_u32 s26, s24, 0x30000
	s_addc_u32 s27, s25, 0
	s_nop 0
	global_store_dwordx4 v156, v[164:167], s[26:27] sc1
	s_nop 1
	s_waitcnt vmcnt(19)
	v_pk_fma_f32 v[170:171], v[76:77], v[140:141], v[170:171]
	v_pk_fma_f32 v[168:169], v[74:75], v[138:139], v[168:169]
	s_add_u32 s26, s24, 0x30040
	s_addc_u32 s27, s25, 0
	s_nop 0
	global_store_dwordx4 v156, v[168:171], s[26:27] sc1
	s_nop 1
	s_waitcnt vmcnt(19)
	v_pk_fma_f32 v[174:175], v[72:73], v[136:137], v[174:175]
	v_pk_fma_f32 v[172:173], v[70:71], v[134:135], v[172:173]
	s_add_u32 s26, s24, 0x30200
	s_addc_u32 s27, s25, 0
	s_nop 0
	global_store_dwordx4 v156, v[172:175], s[26:27] sc1
	s_nop 1
	s_waitcnt vmcnt(19)
	v_pk_fma_f32 v[178:179], v[68:69], v[132:133], v[178:179]
	v_pk_fma_f32 v[176:177], v[66:67], v[130:131], v[176:177]
	s_add_u32 s26, s24, 0x30240
	s_addc_u32 s27, s25, 0
	s_nop 0
	global_store_dwordx4 v156, v[176:179], s[26:27] sc1
	s_nop 1
	v_add_co_u32_e32 v148, vcc, 0xa0000, v146
	s_nop 1
	v_addc_co_u32_e32 v149, vcc, 0, v147, vcc
	global_load_dwordx4 v[164:167], v[148:149], off
	global_load_dwordx4 v[168:171], v[148:149], off offset:64
	global_load_dwordx4 v[172:175], v[148:149], off offset:512
	global_load_dwordx4 v[176:179], v[148:149], off offset:576
	s_waitcnt vmcnt(19)
	v_pk_fma_f32 v[182:183], v[64:65], v[144:145], v[182:183]
	v_pk_fma_f32 v[180:181], v[62:63], v[142:143], v[180:181]
	s_add_u32 s26, s24, 0x80000
	s_addc_u32 s27, s25, 0
	s_nop 0
	global_store_dwordx4 v156, v[180:183], s[26:27] sc1
	s_nop 1
	s_waitcnt vmcnt(19)
	v_pk_fma_f32 v[186:187], v[60:61], v[140:141], v[186:187]
	v_pk_fma_f32 v[184:185], v[58:59], v[138:139], v[184:185]
	s_add_u32 s26, s24, 0x80040
	s_addc_u32 s27, s25, 0
	s_nop 0
	global_store_dwordx4 v156, v[184:187], s[26:27] sc1
	s_nop 1
	s_waitcnt vmcnt(19)
	v_pk_fma_f32 v[190:191], v[56:57], v[136:137], v[190:191]
	v_pk_fma_f32 v[188:189], v[54:55], v[134:135], v[188:189]
	s_add_u32 s26, s24, 0x80200
	s_addc_u32 s27, s25, 0
	s_nop 0
	global_store_dwordx4 v156, v[188:191], s[26:27] sc1
	s_nop 1
	s_waitcnt vmcnt(19)
	v_pk_fma_f32 v[194:195], v[52:53], v[132:133], v[194:195]
	v_pk_fma_f32 v[192:193], v[50:51], v[130:131], v[192:193]
	s_add_u32 s26, s24, 0x80240
	s_addc_u32 s27, s25, 0
	s_nop 0
	global_store_dwordx4 v156, v[192:195], s[26:27] sc1
	s_nop 1
	v_add_co_u32_e32 v148, vcc, 0xb0000, v146
	s_nop 1
	v_addc_co_u32_e32 v149, vcc, 0, v147, vcc
	global_load_dwordx4 v[180:183], v[148:149], off
	global_load_dwordx4 v[184:187], v[148:149], off offset:64
	global_load_dwordx4 v[188:191], v[148:149], off offset:512
	global_load_dwordx4 v[192:195], v[148:149], off offset:576
	s_waitcnt vmcnt(19)
	v_pk_fma_f32 v[198:199], v[48:49], v[144:145], v[198:199]
	v_pk_fma_f32 v[196:197], v[46:47], v[142:143], v[196:197]
	s_add_u32 s26, s24, 0x90000
	s_addc_u32 s27, s25, 0
	s_nop 0
	global_store_dwordx4 v156, v[196:199], s[26:27] sc1
	s_nop 1
	s_waitcnt vmcnt(19)
	v_pk_fma_f32 v[202:203], v[44:45], v[140:141], v[202:203]
	v_pk_fma_f32 v[200:201], v[42:43], v[138:139], v[200:201]
	s_add_u32 s26, s24, 0x90040
	s_addc_u32 s27, s25, 0
	s_nop 0
	global_store_dwordx4 v156, v[200:203], s[26:27] sc1
	s_nop 1
	s_waitcnt vmcnt(19)
	v_pk_fma_f32 v[206:207], v[40:41], v[136:137], v[206:207]
	v_pk_fma_f32 v[204:205], v[38:39], v[134:135], v[204:205]
	s_add_u32 s26, s24, 0x90200
	s_addc_u32 s27, s25, 0
	s_nop 0
	global_store_dwordx4 v156, v[204:207], s[26:27] sc1
	s_nop 1
	s_waitcnt vmcnt(19)
	v_pk_fma_f32 v[210:211], v[36:37], v[132:133], v[210:211]
	v_pk_fma_f32 v[208:209], v[34:35], v[130:131], v[208:209]
	s_add_u32 s26, s24, 0x90240
	s_addc_u32 s27, s25, 0
	s_nop 0
	global_store_dwordx4 v156, v[208:211], s[26:27] sc1
	s_nop 1
	s_waitcnt vmcnt(15)
	v_pk_fma_f32 v[166:167], v[32:33], v[144:145], v[166:167]
	v_pk_fma_f32 v[164:165], v[30:31], v[142:143], v[164:165]
	s_add_u32 s26, s24, 0xa0000
	s_addc_u32 s27, s25, 0
	s_nop 0
	global_store_dwordx4 v156, v[164:167], s[26:27] sc1
	s_nop 1
	s_waitcnt vmcnt(15)
	v_pk_fma_f32 v[170:171], v[28:29], v[140:141], v[170:171]
	v_pk_fma_f32 v[168:169], v[26:27], v[138:139], v[168:169]
	s_add_u32 s26, s24, 0xa0040
	s_addc_u32 s27, s25, 0
	s_nop 0
	global_store_dwordx4 v156, v[168:171], s[26:27] sc1
	s_nop 1
	s_waitcnt vmcnt(15)
	v_pk_fma_f32 v[174:175], v[24:25], v[136:137], v[174:175]
	v_pk_fma_f32 v[172:173], v[22:23], v[134:135], v[172:173]
	s_add_u32 s26, s24, 0xa0200
	s_addc_u32 s27, s25, 0
	s_nop 0
	global_store_dwordx4 v156, v[172:175], s[26:27] sc1
	s_nop 1
	s_waitcnt vmcnt(15)
	v_pk_fma_f32 v[178:179], v[20:21], v[132:133], v[178:179]
	v_pk_fma_f32 v[176:177], v[18:19], v[130:131], v[176:177]
	s_add_u32 s26, s24, 0xa0240
	s_addc_u32 s27, s25, 0
	s_nop 0
	global_store_dwordx4 v156, v[176:179], s[26:27] sc1
	s_nop 1
	s_waitcnt vmcnt(11)
	v_pk_fma_f32 v[182:183], v[16:17], v[144:145], v[182:183]
	v_pk_fma_f32 v[180:181], v[14:15], v[142:143], v[180:181]
	s_add_u32 s26, s24, 0xb0000
	s_addc_u32 s27, s25, 0
	s_nop 0
	global_store_dwordx4 v156, v[180:183], s[26:27] sc1
	s_nop 1
	s_waitcnt vmcnt(11)
	v_pk_fma_f32 v[186:187], v[12:13], v[140:141], v[186:187]
	v_pk_fma_f32 v[184:185], v[10:11], v[138:139], v[184:185]
	s_add_u32 s26, s24, 0xb0040
	s_addc_u32 s27, s25, 0
	s_nop 0
	global_store_dwordx4 v156, v[184:187], s[26:27] sc1
	s_nop 1
	s_waitcnt vmcnt(11)
	v_pk_fma_f32 v[190:191], v[8:9], v[136:137], v[190:191]
	v_pk_fma_f32 v[188:189], v[6:7], v[134:135], v[188:189]
	s_add_u32 s26, s24, 0xb0200
	s_addc_u32 s27, s25, 0
	s_nop 0
	global_store_dwordx4 v156, v[188:191], s[26:27] sc1
	s_nop 1
	s_waitcnt vmcnt(11)
	v_pk_fma_f32 v[194:195], v[4:5], v[132:133], v[194:195]
	v_pk_fma_f32 v[192:193], v[2:3], v[130:131], v[192:193]
	s_add_u32 s26, s24, 0xb0240
	s_addc_u32 s27, s25, 0
	s_nop 0
	global_store_dwordx4 v156, v[192:195], s[26:27] sc1
	s_nop 1
	s_mov_b64 s[24:25], 0

;   DI void operator()(const f4 (&acc)[2][2][4][2], const GUnit& u, int wr, int wc, int fr, int fq) const {
;     ...
;     const int g0 = row0_of(u.pm, isctx ? 2 : 1), b = g0 / TOK, t0 = g0 - b * TOK;
;     const int col0 = u.pn * 256 + wc * 32;
;     const size_t rowoff = (size_t)(wr * 64) * 1024 + col0;
;     const char* src = (const char*)(xl_src + ((size_t)b * SEQ + (isctx ? 0 : t0)) * 1024 + rowoff);
;     char* dst = (char*)(xl_dst + ((size_t)b * SEQ + (isctx ? 0 : t0)) * 1024 + rowoff);
;     const char* gt = (const char*)(mods_l + (size_t)(isctx ? 16 : b) * 6144 + gt_off + col0);
;     const unsigned lo = (unsigned)(fr * 1024 + 4 * fq) * 4u, glo = (unsigned)(4 * fq) * 4u;
;     f4 gv[2][2];
; #pragma unroll
;     for (int bj = 0; bj < 2; ++bj)
; #pragma unroll
;       for (int n = 0; n < 2; ++n) gv[bj][n] = *(const f4*)(gt + (bj * 128 + n * 16) * 4 + glo);
;     if (!isctx) {
; #pragma unroll
;       for (int ai = 0; ai < 2; ++ai)
; #pragma unroll
;         for (int mh = 0; mh < 2; ++mh) {
;           f4 xv[2][2][2];
; #pragma unroll
;           for (int mm = 0; mm < 2; ++mm)
; #pragma unroll
;             for (int bj = 0; bj < 2; ++bj)
; #pragma unroll
;               for (int n = 0; n < 2; ++n)
;                 xv[mm][bj][n] = *(const f4*)(src + ((size_t)(ai * 128 + (mh * 2 + mm) * 16) * 1024 + bj * 128 + n * 16) * 4 + lo);
; #pragma unroll
;           for (int mm = 0; mm < 2; ++mm)
; #pragma unroll
;             for (int bj = 0; bj < 2; ++bj)
; #pragma unroll
;               for (int n = 0; n < 2; ++n)
;                 wt16(dst + ((size_t)(ai * 128 + (mh * 2 + mm) * 16) * 1024 + bj * 128 + n * 16) * 4, lo, as_u4(xv[mm][bj][n] + gv[bj][n] * acc[ai][bj][mh * 2 + mm][n]));
;         }
.LBB0_2663:
	s_mul_hi_i32 s20, s24, 0x38e38e39
	s_lshr_b32 s21, s20, 31
	s_ashr_i32 s20, s20, 9
	s_add_i32 s20, s20, s21
	s_lshl_b32 s19, s19, 8
	s_mul_i32 s21, s20, 0xfffff700
	s_or_b32 s28, s19, s68
	s_add_i32 s24, s21, s24
	s_ashr_i32 s29, s28, 31
	s_ashr_i32 s21, s20, 31
	s_and_b64 s[22:23], exec, s[22:23]
	s_cselect_b32 s19, 16, s20
	s_mul_hi_i32 s22, s19, 0x6000
	s_mulk_i32 s19, 0x6000
	s_add_u32 s19, s38, s19
	s_addc_u32 s25, s39, s22
	s_lshl_b64 s[22:23], s[28:29], 2
	s_add_u32 s40, s19, s22
	s_addc_u32 s41, s25, s23
	s_waitcnt vmcnt(0)
	v_lshl_add_u64 v[130:131], s[40:41], 0, v[154:155]
	s_mov_b64 s[40:41], 0x5000
	v_lshl_add_u64 v[132:133], v[130:131], 0, s[40:41]
	v_add_co_u32_e32 v130, vcc, 0x5000, v130
	s_nop 1
	v_addc_co_u32_e32 v131, vcc, 0, v131, vcc
	global_load_dwordx4 v[138:141], v[132:133], off offset:64
	global_load_dwordx4 v[134:137], v[132:133], off offset:512
	global_load_dwordx4 v[142:145], v[130:131], off
	s_nop 0
	global_load_dwordx4 v[130:133], v[132:133], off offset:576
	s_andn2_b64 vcc, exec, s[26:27]
	s_mov_b64 s[26:27], -1
	s_cbranch_vccnz .LBB0_2665
	s_ashr_i32 s25, s24, 31
	s_lshl_b64 s[26:27], s[24:25], 10
	s_lshl_b64 s[40:41], s[20:21], 21
	s_add_u32 s26, s26, s40
	s_addc_u32 s27, s27, s41
	s_lshl_b64 s[40:41], s[26:27], 2
	s_waitcnt lgkmcnt(0)
	s_add_u32 s19, s4, s40
	s_addc_u32 s25, s5, s41
	s_add_u32 s26, s8, s28
	s_addc_u32 s27, s9, s29
	s_lshl_b64 s[28:29], s[26:27], 2
	s_add_u32 s26, s19, s28
	s_addc_u32 s27, s25, s29
	s_add_u32 s19, s2, s40
	s_addc_u32 s25, s3, s41
	s_add_u32 s28, s19, s28
	s_addc_u32 s29, s25, s29
	v_lshl_add_u64 v[146:147], s[28:29], 0, v[156:157]
	global_load_dwordx4 v[164:167], v[146:147], off
	global_load_dwordx4 v[168:171], v[146:147], off offset:64
	global_load_dwordx4 v[172:175], v[146:147], off offset:512
	global_load_dwordx4 v[176:179], v[146:147], off offset:576
	v_add_co_u32_e32 v148, vcc, 0x10000, v146
	s_nop 1
	v_addc_co_u32_e32 v149, vcc, 0, v147, vcc
	global_load_dwordx4 v[180:183], v[148:149], off
	global_load_dwordx4 v[184:187], v[148:149], off offset:64
	global_load_dwordx4 v[188:191], v[148:149], off offset:512
	global_load_dwordx4 v[192:195], v[148:149], off offset:576
	v_add_co_u32_e32 v148, vcc, 0x20000, v146
	s_nop 1
	v_addc_co_u32_e32 v149, vcc, 0, v147, vcc
	global_load_dwordx4 v[196:199], v[148:149], off
	global_load_dwordx4 v[200:203], v[148:149], off offset:64
	global_load_dwordx4 v[204:207], v[148:149], off offset:512
	global_load_dwordx4 v[208:211], v[148:149], off offset:576
	s_waitcnt vmcnt(11)
	v_pk_fma_f32 v[166:167], v[128:129], v[144:145], v[166:167]
	v_pk_fma_f32 v[164:165], v[126:127], v[142:143], v[164:165]
	s_nop 0
	global_store_dwordx4 v156, v[164:167], s[26:27] sc1
	s_nop 1
	s_waitcnt vmcnt(11)
	v_pk_fma_f32 v[170:171], v[124:125], v[140:141], v[170:171]
	v_pk_fma_f32 v[168:169], v[122:123], v[138:139], v[168:169]
	s_add_u32 s28, s26, 0x40
	s_addc_u32 s29, s27, 0
	s_nop 0
	global_store_dwordx4 v156, v[168:171], s[28:29] sc1
	s_nop 1
	s_waitcnt vmcnt(11)
	v_pk_fma_f32 v[174:175], v[120:121], v[136:137], v[174:175]
	v_pk_fma_f32 v[172:173], v[118:119], v[134:135], v[172:173]
	s_add_u32 s28, s26, 0x200
	s_addc_u32 s29, s27, 0
	s_nop 0
	global_store_dwordx4 v156, v[172:175], s[28:29] sc1
	s_nop 1
	s_waitcnt vmcnt(11)
	v_pk_fma_f32 v[178:179], v[116:117], v[132:133], v[178:179]
	v_pk_fma_f32 v[176:177], v[114:115], v[130:131], v[176:177]
	s_add_u32 s28, s26, 0x240
	s_addc_u32 s29, s27, 0
	s_nop 0
	global_store_dwordx4 v156, v[176:179], s[28:29] sc1
	s_nop 1
	v_add_co_u32_e32 v148, vcc, 0x30000, v146
	s_nop 1
	v_addc_co_u32_e32 v149, vcc, 0, v147, vcc
	global_load_dwordx4 v[164:167], v[148:149], off
	global_load_dwordx4 v[168:171], v[148:149], off offset:64
	global_load_dwordx4 v[172:175], v[148:149], off offset:512
	global_load_dwordx4 v[176:179], v[148:149], off offset:576
	s_waitcnt vmcnt(15)
	v_pk_fma_f32 v[182:183], v[112:113], v[144:145], v[182:183]
	v_pk_fma_f32 v[180:181], v[110:111], v[142:143], v[180:181]
	s_add_u32 s28, s26, 0x10000
	s_addc_u32 s29, s27, 0
	s_nop 0
	global_store_dwordx4 v156, v[180:183], s[28:29] sc1
	s_nop 1
	s_waitcnt vmcnt(15)
	v_pk_fma_f32 v[186:187], v[108:109], v[140:141], v[186:187]
	v_pk_fma_f32 v[184:185], v[106:107], v[138:139], v[184:185]
	s_add_u32 s28, s26, 0x10040
	s_addc_u32 s29, s27, 0
	s_nop 0
	global_store_dwordx4 v156, v[184:187], s[28:29] sc1
	s_nop 1
	s_waitcnt vmcnt(15)
	v_pk_fma_f32 v[190:191], v[104:105], v[136:137], v[190:191]
	v_pk_fma_f32 v[188:189], v[102:103], v[134:135], v[188:189]
	s_add_u32 s28, s26, 0x10200
	s_addc_u32 s29, s27, 0
	s_nop 0
	global_store_dwordx4 v156, v[188:191], s[28:29] sc1
	s_nop 1
	s_waitcnt vmcnt(15)
	v_pk_fma_f32 v[194:195], v[100:101], v[132:133], v[194:195]
	v_pk_fma_f32 v[192:193], v[98:99], v[130:131], v[192:193]
	s_add_u32 s28, s26, 0x10240
	s_addc_u32 s29, s27, 0
	s_nop 0
	global_store_dwordx4 v156, v[192:195], s[28:29] sc1
	s_nop 1
	v_add_co_u32_e32 v148, vcc, 0x80000, v146
	s_nop 1
	v_addc_co_u32_e32 v149, vcc, 0, v147, vcc
	global_load_dwordx4 v[180:183], v[148:149], off
	global_load_dwordx4 v[184:187], v[148:149], off offset:64
	global_load_dwordx4 v[188:191], v[148:149], off offset:512
	global_load_dwordx4 v[192:195], v[148:149], off offset:576
	s_waitcnt vmcnt(19)
	v_pk_fma_f32 v[198:199], v[96:97], v[144:145], v[198:199]
	v_pk_fma_f32 v[196:197], v[94:95], v[142:143], v[196:197]
	s_add_u32 s28, s26, 0x20000
	s_addc_u32 s29, s27, 0
	s_nop 0
	global_store_dwordx4 v156, v[196:199], s[28:29] sc1
	s_nop 1
	s_waitcnt vmcnt(19)
;   DI void operator()(const f4 (&acc)[2][2][4][2], const GUnit& u, int wr, int wc, int fr, int fq) const {
;     ...
;     if (!isctx) {
; #pragma unroll
;       for (int ai = 0; ai < 2; ++ai)
; #pragma unroll
;         for (int mh = 0; mh < 2; ++mh) {
;           f4 xv[2][2][2];
; #pragma unroll
;           for (int mm = 0; mm < 2; ++mm)
; #pragma unroll
;             for (int bj = 0; bj < 2; ++bj)
; #pragma unroll
;               for (int n = 0; n < 2; ++n)
;                 xv[mm][bj][n] = *(const f4*)(src + ((size_t)(ai * 128 + (mh * 2 + mm) * 16) * 1024 + bj * 128 + n * 16) * 4 + lo);
; #pragma unroll
;           for (int mm = 0; mm < 2; ++mm)
; #pragma unroll
;             for (int bj = 0; bj < 2; ++bj)
; #pragma unroll
;               for (int n = 0; n < 2; ++n)
;                 wt16(dst + ((size_t)(ai * 128 + (mh * 2 + mm) * 16) * 1024 + bj * 128 + n * 16) * 4, lo, as_u4(xv[mm][bj][n] + gv[bj][n] * acc[ai][bj][mh * 2 + mm][n]));
;         }
	v_pk_fma_f32 v[202:203], v[92:93], v[140:141], v[202:203]
	v_pk_fma_f32 v[200:201], v[90:91], v[138:139], v[200:201]
	s_add_u32 s28, s26, 0x20040
	s_addc_u32 s29, s27, 0
	s_nop 0
	global_store_dwordx4 v156, v[200:203], s[28:29] sc1
	s_nop 1
	s_waitcnt vmcnt(19)
	v_pk_fma_f32 v[206:207], v[88:89], v[136:137], v[206:207]
	v_pk_fma_f32 v[204:205], v[86:87], v[134:135], v[204:205]
	s_add_u32 s28, s26, 0x20200
	s_addc_u32 s29, s27, 0
	s_nop 0
	global_store_dwordx4 v156, v[204:207], s[28:29] sc1
	s_nop 1
	s_waitcnt vmcnt(19)
	v_pk_fma_f32 v[210:211], v[84:85], v[132:133], v[210:211]
	v_pk_fma_f32 v[208:209], v[82:83], v[130:131], v[208:209]
	s_add_u32 s28, s26, 0x20240
	s_addc_u32 s29, s27, 0
	s_nop 0
	global_store_dwordx4 v156, v[208:211], s[28:29] sc1
	s_nop 1
	v_add_co_u32_e32 v148, vcc, 0x90000, v146
	s_nop 1
	v_addc_co_u32_e32 v149, vcc, 0, v147, vcc
	global_load_dwordx4 v[196:199], v[148:149], off
	global_load_dwordx4 v[200:203], v[148:149], off offset:64
	global_load_dwordx4 v[204:207], v[148:149], off offset:512
	global_load_dwordx4 v[208:211], v[148:149], off offset:576
	s_waitcnt vmcnt(19)
	v_pk_fma_f32 v[166:167], v[80:81], v[144:145], v[166:167]
	v_pk_fma_f32 v[164:165], v[78:79], v[142:143], v[164:165]
	s_add_u32 s28, s26, 0x30000
	s_addc_u32 s29, s27, 0
	s_nop 0
	global_store_dwordx4 v156, v[164:167], s[28:29] sc1
	s_nop 1
	s_waitcnt vmcnt(19)
	v_pk_fma_f32 v[170:171], v[76:77], v[140:141], v[170:171]
	v_pk_fma_f32 v[168:169], v[74:75], v[138:139], v[168:169]
	s_add_u32 s28, s26, 0x30040
	s_addc_u32 s29, s27, 0
	s_nop 0
	global_store_dwordx4 v156, v[168:171], s[28:29] sc1
	s_nop 1
	s_waitcnt vmcnt(19)
	v_pk_fma_f32 v[174:175], v[72:73], v[136:137], v[174:175]
	v_pk_fma_f32 v[172:173], v[70:71], v[134:135], v[172:173]
	s_add_u32 s28, s26, 0x30200
	s_addc_u32 s29, s27, 0
	s_nop 0
	global_store_dwordx4 v156, v[172:175], s[28:29] sc1
	s_nop 1
	s_waitcnt vmcnt(19)
	v_pk_fma_f32 v[178:179], v[68:69], v[132:133], v[178:179]
	v_pk_fma_f32 v[176:177], v[66:67], v[130:131], v[176:177]
	s_add_u32 s28, s26, 0x30240
	s_addc_u32 s29, s27, 0
	s_nop 0
	global_store_dwordx4 v156, v[176:179], s[28:29] sc1
	s_nop 1
	v_add_co_u32_e32 v148, vcc, 0xa0000, v146
	s_nop 1
	v_addc_co_u32_e32 v149, vcc, 0, v147, vcc
	global_load_dwordx4 v[164:167], v[148:149], off
	global_load_dwordx4 v[168:171], v[148:149], off offset:64
	global_load_dwordx4 v[172:175], v[148:149], off offset:512
	global_load_dwordx4 v[176:179], v[148:149], off offset:576
	s_waitcnt vmcnt(19)
	v_pk_fma_f32 v[182:183], v[64:65], v[144:145], v[182:183]
	v_pk_fma_f32 v[180:181], v[62:63], v[142:143], v[180:181]
	s_add_u32 s28, s26, 0x80000
	s_addc_u32 s29, s27, 0
	s_nop 0
	global_store_dwordx4 v156, v[180:183], s[28:29] sc1
	s_nop 1
	s_waitcnt vmcnt(19)
	v_pk_fma_f32 v[186:187], v[60:61], v[140:141], v[186:187]
	v_pk_fma_f32 v[184:185], v[58:59], v[138:139], v[184:185]
	s_add_u32 s28, s26, 0x80040
	s_addc_u32 s29, s27, 0
	s_nop 0
	global_store_dwordx4 v156, v[184:187], s[28:29] sc1
	s_nop 1
	s_waitcnt vmcnt(19)
	v_pk_fma_f32 v[190:191], v[56:57], v[136:137], v[190:191]
	v_pk_fma_f32 v[188:189], v[54:55], v[134:135], v[188:189]
	s_add_u32 s28, s26, 0x80200
	s_addc_u32 s29, s27, 0
	s_nop 0
	global_store_dwordx4 v156, v[188:191], s[28:29] sc1
	s_nop 1
	s_waitcnt vmcnt(19)
	v_pk_fma_f32 v[194:195], v[52:53], v[132:133], v[194:195]
	v_pk_fma_f32 v[192:193], v[50:51], v[130:131], v[192:193]
	s_add_u32 s28, s26, 0x80240
	s_addc_u32 s29, s27, 0
	s_nop 0
	global_store_dwordx4 v156, v[192:195], s[28:29] sc1
	s_nop 1
	v_add_co_u32_e32 v148, vcc, 0xb0000, v146
	s_nop 1
	v_addc_co_u32_e32 v149, vcc, 0, v147, vcc
	global_load_dwordx4 v[180:183], v[148:149], off
	global_load_dwordx4 v[184:187], v[148:149], off offset:64
	global_load_dwordx4 v[188:191], v[148:149], off offset:512
	global_load_dwordx4 v[192:195], v[148:149], off offset:576
	s_waitcnt vmcnt(19)
	v_pk_fma_f32 v[198:199], v[48:49], v[144:145], v[198:199]
	v_pk_fma_f32 v[196:197], v[46:47], v[142:143], v[196:197]
	s_add_u32 s28, s26, 0x90000
	s_addc_u32 s29, s27, 0
	s_nop 0
	global_store_dwordx4 v156, v[196:199], s[28:29] sc1
	s_nop 1
	s_waitcnt vmcnt(19)
	v_pk_fma_f32 v[202:203], v[44:45], v[140:141], v[202:203]
	v_pk_fma_f32 v[200:201], v[42:43], v[138:139], v[200:201]
	s_add_u32 s28, s26, 0x90040
	s_addc_u32 s29, s27, 0
	s_nop 0
	global_store_dwordx4 v156, v[200:203], s[28:29] sc1
	s_nop 1
	s_waitcnt vmcnt(19)
	v_pk_fma_f32 v[206:207], v[40:41], v[136:137], v[206:207]
	v_pk_fma_f32 v[204:205], v[38:39], v[134:135], v[204:205]
	s_add_u32 s28, s26, 0x90200
	s_addc_u32 s29, s27, 0
	s_nop 0
	global_store_dwordx4 v156, v[204:207], s[28:29] sc1
	s_nop 1
	s_waitcnt vmcnt(19)
	v_pk_fma_f32 v[210:211], v[36:37], v[132:133], v[210:211]
	v_pk_fma_f32 v[208:209], v[34:35], v[130:131], v[208:209]
	s_add_u32 s28, s26, 0x90240
	s_addc_u32 s29, s27, 0
	s_nop 0
	global_store_dwordx4 v156, v[208:211], s[28:29] sc1
	s_nop 1
	s_waitcnt vmcnt(15)
	v_pk_fma_f32 v[166:167], v[32:33], v[144:145], v[166:167]
	v_pk_fma_f32 v[164:165], v[30:31], v[142:143], v[164:165]
	s_add_u32 s28, s26, 0xa0000
	s_addc_u32 s29, s27, 0
	s_nop 0
	global_store_dwordx4 v156, v[164:167], s[28:29] sc1
	s_nop 1
	s_waitcnt vmcnt(15)
	v_pk_fma_f32 v[170:171], v[28:29], v[140:141], v[170:171]
	v_pk_fma_f32 v[168:169], v[26:27], v[138:139], v[168:169]
	s_add_u32 s28, s26, 0xa0040
	s_addc_u32 s29, s27, 0
	s_nop 0
	global_store_dwordx4 v156, v[168:171], s[28:29] sc1
	s_nop 1
	s_waitcnt vmcnt(15)
	v_pk_fma_f32 v[174:175], v[24:25], v[136:137], v[174:175]
	v_pk_fma_f32 v[172:173], v[22:23], v[134:135], v[172:173]
	s_add_u32 s28, s26, 0xa0200
	s_addc_u32 s29, s27, 0
	s_nop 0
	global_store_dwordx4 v156, v[172:175], s[28:29] sc1
	s_nop 1
	s_waitcnt vmcnt(15)
	v_pk_fma_f32 v[178:179], v[20:21], v[132:133], v[178:179]
	v_pk_fma_f32 v[176:177], v[18:19], v[130:131], v[176:177]
	s_add_u32 s28, s26, 0xa0240
	s_addc_u32 s29, s27, 0
	s_nop 0
	global_store_dwordx4 v156, v[176:179], s[28:29] sc1
	s_nop 1
	s_waitcnt vmcnt(11)
	v_pk_fma_f32 v[182:183], v[16:17], v[144:145], v[182:183]
	v_pk_fma_f32 v[180:181], v[14:15], v[142:143], v[180:181]
	s_add_u32 s28, s26, 0xb0000
	s_addc_u32 s29, s27, 0
	s_nop 0
	global_store_dwordx4 v156, v[180:183], s[28:29] sc1
	s_nop 1
	s_waitcnt vmcnt(11)
	v_pk_fma_f32 v[186:187], v[12:13], v[140:141], v[186:187]
	v_pk_fma_f32 v[184:185], v[10:11], v[138:139], v[184:185]
	s_add_u32 s28, s26, 0xb0040
	s_addc_u32 s29, s27, 0
	s_nop 0
	global_store_dwordx4 v156, v[184:187], s[28:29] sc1
	s_nop 1
	s_waitcnt vmcnt(11)
	v_pk_fma_f32 v[190:191], v[8:9], v[136:137], v[190:191]
	v_pk_fma_f32 v[188:189], v[6:7], v[134:135], v[188:189]
	s_add_u32 s28, s26, 0xb0200
	s_addc_u32 s29, s27, 0
	s_nop 0
	global_store_dwordx4 v156, v[188:191], s[28:29] sc1
	s_nop 1
	s_waitcnt vmcnt(11)
	v_pk_fma_f32 v[194:195], v[4:5], v[132:133], v[194:195]
	v_pk_fma_f32 v[192:193], v[2:3], v[130:131], v[192:193]
	s_add_u32 s28, s26, 0xb0240
	s_addc_u32 s29, s27, 0
	s_nop 0
	global_store_dwordx4 v156, v[192:195], s[28:29] sc1
	s_nop 1
	s_mov_b64 s[26:27], 0
